# speedup vs baseline: 1.0050x; 1.0050x over previous
; #define DSR(dst, addr, OFF) asm volatile("ds_read_b128 %0, %1 offset:%2" : "=&v"(dst) : "v"(addr), "i"(OFF) : "memory")
; template <int EPI>
; __device__ __forceinline__ void gemm_phase(const Params& p, const u16* __restrict__ A, const u16* __restrict__ Bt, int K, int nN,
;                            u16* __restrict__ Cout, int ldc) {
;     ...
;       bf16x8 Ar[3], Bq[2][4];
;       const unsigned la_u = lds0 + (unsigned)(cur * STAGE_B + aoff), lb_u = lds0 + (unsigned)(cur * STAGE_B + boff);
;     ...
;       DSR(Bq[0][0], lb_u, 0); DSR(Bq[0][1], lb_u, 2048); DSR(Bq[0][2], lb_u, 4096); DSR(Bq[0][3], lb_u, 6144);
;       DSR(Ar[0], la_u, 0); DSR(Ar[1], la_u, 2048);
;     ...
;       GSTEP(0, 2); GSTEP(1, 6); GSTEP(2, 6); GSTEP(3, 6); GSTEP(4, 2); GSTEP(5, 2); GSTEP(6, 2); GSTEP(7, 2);
;       GSTEP(8, 2); GSTEP(9, 2); GSTEP(10, 2); GSTEP(11, 2); GSTEP(12, 2); GSTEP(13, 2); GSTEP(14, 1); GSTEP(15, 0);
.LBB0_859:
	ds_read_b128 v[0:3], v194 offset:0
	ds_read_b128 v[4:7], v194 offset:0x800
	ds_read_b128 v[8:11], v194 offset:0x1000
	ds_read_b128 v[12:15], v194 offset:0x1800
	ds_read_b128 v[16:19], v193 offset:0
	ds_read_b128 v[20:23], v193 offset:0x800
	ds_read_b128 v[24:27], v193 offset:0x1000
	s_waitcnt lgkmcnt(2)
	s_setprio 1
	v_mfma_f32_16x16x32_bf16 v[28:31], v[16:19], v[0:3], 0
	v_mfma_f32_16x16x32_bf16 v[32:35], v[16:19], v[4:7], 0
	v_mfma_f32_16x16x32_bf16 v[36:39], v[16:19], v[8:11], 0
	v_mfma_f32_16x16x32_bf16 v[16:19], v[16:19], v[12:15], 0
	s_setprio 0
	v_mov_b32_e32 v40, v176
	v_mov_b32_e32 v41, v172
	v_lshl_add_u64 v[40:41], v[40:41], 1, s[30:31]
	v_readfirstlane_b32 s17, v198
	v_lshl_add_u64 v[40:41], v[40:41], 0, s[62:63]
	s_mov_b32 m0, s17
	s_nop 0
	global_load_lds_dwordx4 v[40:41], off
	ds_read_b128 v[40:43], v193 offset:0x1800
	ds_read_b128 v[130:133], v194 offset:0x400
	ds_read_b128 v[134:137], v194 offset:0xc00
	ds_read_b128 v[138:141], v194 offset:0x1400
	ds_read_b128 v[142:145], v194 offset:0x1c00
	s_waitcnt lgkmcnt(6)
	s_setprio 1
	v_mfma_f32_16x16x32_bf16 v[44:47], v[20:23], v[0:3], 0
	v_mfma_f32_16x16x32_bf16 v[48:51], v[20:23], v[4:7], 0
	v_mfma_f32_16x16x32_bf16 v[52:55], v[20:23], v[8:11], 0
	v_mfma_f32_16x16x32_bf16 v[20:23], v[20:23], v[12:15], 0
	s_setprio 0
	v_mov_b32_e32 v56, v178
	v_mov_b32_e32 v57, v172
	v_lshl_add_u64 v[56:57], v[56:57], 1, s[30:31]
	v_readfirstlane_b32 s17, v199
	v_lshl_add_u64 v[56:57], v[56:57], 0, s[62:63]
	s_mov_b32 m0, s17
	s_nop 0
	global_load_lds_dwordx4 v[56:57], off
	ds_read_b128 v[56:59], v193 offset:0x2000
	s_waitcnt lgkmcnt(6)
	s_setprio 1
	v_mfma_f32_16x16x32_bf16 v[60:63], v[24:27], v[0:3], 0
	v_mfma_f32_16x16x32_bf16 v[64:67], v[24:27], v[4:7], 0
	v_mfma_f32_16x16x32_bf16 v[68:71], v[24:27], v[8:11], 0
	v_mfma_f32_16x16x32_bf16 v[24:27], v[24:27], v[12:15], 0
	s_setprio 0
	v_mov_b32_e32 v72, v180
	v_mov_b32_e32 v73, v172
	v_lshl_add_u64 v[72:73], v[72:73], 1, s[30:31]
	v_readfirstlane_b32 s17, v200
	v_lshl_add_u64 v[72:73], v[72:73], 0, s[62:63]
	s_mov_b32 m0, s17
	s_nop 0
	global_load_lds_dwordx4 v[72:73], off
	ds_read_b128 v[72:75], v193 offset:0x2800
	s_waitcnt lgkmcnt(6)
	s_setprio 1
	v_mfma_f32_16x16x32_bf16 v[76:79], v[40:43], v[0:3], 0
	v_mfma_f32_16x16x32_bf16 v[146:149], v[40:43], v[4:7], 0
	v_mfma_f32_16x16x32_bf16 v[150:153], v[40:43], v[8:11], 0
	v_mfma_f32_16x16x32_bf16 v[40:43], v[40:43], v[12:15], 0
	s_setprio 0
	v_mov_b32_e32 v80, v191
	v_mov_b32_e32 v81, v172
	v_lshl_add_u64 v[80:81], v[80:81], 1, s[30:31]
	v_readfirstlane_b32 s17, v201
	v_lshl_add_u64 v[80:81], v[80:81], 0, s[62:63]
	s_mov_b32 m0, s17
	s_nop 0
	global_load_lds_dwordx4 v[80:81], off
	ds_read_b128 v[80:83], v193 offset:0x3000
	s_waitcnt lgkmcnt(2)
	s_setprio 1
	v_mfma_f32_16x16x32_bf16 v[154:157], v[56:59], v[0:3], 0
	v_mfma_f32_16x16x32_bf16 v[158:161], v[56:59], v[4:7], 0
	v_mfma_f32_16x16x32_bf16 v[162:165], v[56:59], v[8:11], 0
	v_mfma_f32_16x16x32_bf16 v[166:169], v[56:59], v[12:15], 0
	s_setprio 0
	v_mov_b32_e32 v56, v176
	v_mov_b32_e32 v57, v172
	v_lshl_add_u64 v[56:57], v[56:57], 1, s[28:29]
	v_readfirstlane_b32 s17, v206
	v_lshl_add_u64 v[56:57], v[56:57], 0, s[62:63]
	s_mov_b32 m0, s17
	s_nop 0
	global_load_lds_dwordx4 v[56:57], off
	ds_read_b128 v[56:59], v193 offset:0x3800
	s_waitcnt lgkmcnt(2)
	s_setprio 1
	v_mfma_f32_16x16x32_bf16 v[208:211], v[72:75], v[0:3], 0
	v_mfma_f32_16x16x32_bf16 v[212:215], v[72:75], v[4:7], 0
	v_mfma_f32_16x16x32_bf16 v[216:219], v[72:75], v[8:11], 0
	v_mfma_f32_16x16x32_bf16 v[220:223], v[72:75], v[12:15], 0
	s_setprio 0
	v_mov_b32_e32 v72, v178
	v_mov_b32_e32 v73, v172
	v_lshl_add_u64 v[72:73], v[72:73], 1, s[28:29]
	v_readfirstlane_b32 s17, v202
	v_lshl_add_u64 v[72:73], v[72:73], 0, s[62:63]
	s_mov_b32 m0, s17
	s_nop 0
	global_load_lds_dwordx4 v[72:73], off
	ds_read_b128 v[72:75], v193 offset:0x400
	s_waitcnt lgkmcnt(2)
	s_setprio 1
	v_mfma_f32_16x16x32_bf16 v[224:227], v[80:83], v[0:3], 0
	v_mfma_f32_16x16x32_bf16 v[228:231], v[80:83], v[4:7], 0
	v_mfma_f32_16x16x32_bf16 v[232:235], v[80:83], v[8:11], 0
	v_mfma_f32_16x16x32_bf16 v[236:239], v[80:83], v[12:15], 0
	s_setprio 0
	v_mov_b32_e32 v80, v180
	v_mov_b32_e32 v81, v172
	v_lshl_add_u64 v[80:81], v[80:81], 1, s[28:29]
	v_readfirstlane_b32 s17, v203
	v_lshl_add_u64 v[80:81], v[80:81], 0, s[62:63]
	s_mov_b32 m0, s17
	s_nop 0
	global_load_lds_dwordx4 v[80:81], off
	ds_read_b128 v[80:83], v193 offset:0xc00
	s_waitcnt lgkmcnt(2)
; __device__ __forceinline__ float rsq_(float x) { return __builtin_amdgcn_rsqf(x); }
; #define WAIT_V(n) asm volatile("s_waitcnt vmcnt(%0)" ::"n"(n) : "memory")
; #define DSR(dst, addr, OFF) asm volatile("ds_read_b128 %0, %1 offset:%2" : "=&v"(dst) : "v"(addr), "i"(OFF) : "memory")
; template <int EPI>
; __device__ __forceinline__ void gemm_phase(const Params& p, const u16* __restrict__ A, const u16* __restrict__ Bt, int K, int nN,
;                            u16* __restrict__ Cout, int ldc) {
;     ...
;     for (int t = 0; t < nt; ++t) {
;       const int cur = t & 1, nb = cur ^ 1;
;       const bool last = (t + 1 == nt);
;       const bool dostage = !last || has_next;
;       const u16* pa = last ? Abn : Ab + (t + 1) * BK;
;       const u16* pb = last ? Bbn : Bb + (t + 1) * BK;
;       bf16x8 Ar[3], Bq[2][4];
;       const unsigned la_u = lds0 + (unsigned)(cur * STAGE_B + aoff), lb_u = lds0 + (unsigned)(cur * STAGE_B + boff);
;     ...
;       DSR(Bq[0][0], lb_u, 0); DSR(Bq[0][1], lb_u, 2048); DSR(Bq[0][2], lb_u, 4096); DSR(Bq[0][3], lb_u, 6144);
;       DSR(Ar[0], la_u, 0); DSR(Ar[1], la_u, 2048);
;     ...
;       GSTEP(0, 2); GSTEP(1, 6); GSTEP(2, 6); GSTEP(3, 6); GSTEP(4, 2); GSTEP(5, 2); GSTEP(6, 2); GSTEP(7, 2);
;       GSTEP(8, 2); GSTEP(9, 2); GSTEP(10, 2); GSTEP(11, 2); GSTEP(12, 2); GSTEP(13, 2); GSTEP(14, 1); GSTEP(15, 0);
;       WAIT_V(0);
;       if (EPI != EPI_SS && t == 0 && tid < 256) rsl[tid] = rsq_(ssv * (1.f / DM) + EPS);
;       __syncthreads();
	s_setprio 1
	v_mfma_f32_16x16x32_bf16 v[0:3], v[56:59], v[0:3], 0
	v_mfma_f32_16x16x32_bf16 v[4:7], v[56:59], v[4:7], 0
	v_mfma_f32_16x16x32_bf16 v[240:243], v[56:59], v[8:11], 0
	v_mfma_f32_16x16x32_bf16 v[244:247], v[56:59], v[12:15], 0
	s_setprio 0
	v_mov_b32_e32 v8, v191
	v_mov_b32_e32 v9, v172
	v_lshl_add_u64 v[8:9], v[8:9], 1, s[28:29]
	v_readfirstlane_b32 s17, v204
	v_lshl_add_u64 v[8:9], v[8:9], 0, s[62:63]
	s_mov_b32 m0, s17
	s_nop 0
	global_load_lds_dwordx4 v[8:9], off
	ds_read_b128 v[8:11], v193 offset:0x1400
	s_waitcnt lgkmcnt(2)
	s_setprio 1
	v_mfma_f32_16x16x32_bf16 v[124:127], v[72:75], v[130:133], v[28:31]
	v_mfma_f32_16x16x32_bf16 v[120:123], v[72:75], v[134:137], v[32:35]
	v_mfma_f32_16x16x32_bf16 v[116:119], v[72:75], v[138:141], v[36:39]
	v_mfma_f32_16x16x32_bf16 v[112:115], v[72:75], v[142:145], v[16:19]
	s_setprio 0
	ds_read_b128 v[12:15], v193 offset:0x1c00
	s_waitcnt lgkmcnt(2)
	s_setprio 1
	v_mfma_f32_16x16x32_bf16 v[108:111], v[80:83], v[130:133], v[44:47]
	v_mfma_f32_16x16x32_bf16 v[104:107], v[80:83], v[134:137], v[48:51]
	v_mfma_f32_16x16x32_bf16 v[100:103], v[80:83], v[138:141], v[52:55]
	v_mfma_f32_16x16x32_bf16 v[96:99], v[80:83], v[142:145], v[20:23]
	s_setprio 0
	ds_read_b128 v[16:19], v193 offset:0x2400
	s_waitcnt lgkmcnt(2)
	s_setprio 1
	v_mfma_f32_16x16x32_bf16 v[92:95], v[8:11], v[130:133], v[60:63]
	v_mfma_f32_16x16x32_bf16 v[88:91], v[8:11], v[134:137], v[64:67]
	v_mfma_f32_16x16x32_bf16 v[84:87], v[8:11], v[138:141], v[68:71]
	v_mfma_f32_16x16x32_bf16 v[80:83], v[8:11], v[142:145], v[24:27]
	s_setprio 0
	ds_read_b128 v[8:11], v193 offset:0x2c00
	s_waitcnt lgkmcnt(2)
	s_setprio 1
	v_mfma_f32_16x16x32_bf16 v[76:79], v[12:15], v[130:133], v[76:79]
	v_mfma_f32_16x16x32_bf16 v[72:75], v[12:15], v[134:137], v[146:149]
	v_mfma_f32_16x16x32_bf16 v[68:71], v[12:15], v[138:141], v[150:153]
	v_mfma_f32_16x16x32_bf16 v[64:67], v[12:15], v[142:145], v[40:43]
	s_setprio 0
	ds_read_b128 v[12:15], v193 offset:0x3400
	s_waitcnt lgkmcnt(2)
	s_setprio 1
	v_mfma_f32_16x16x32_bf16 v[60:63], v[16:19], v[130:133], v[154:157]
	v_mfma_f32_16x16x32_bf16 v[56:59], v[16:19], v[134:137], v[158:161]
	v_mfma_f32_16x16x32_bf16 v[52:55], v[16:19], v[138:141], v[162:165]
	v_mfma_f32_16x16x32_bf16 v[48:51], v[16:19], v[142:145], v[166:169]
	s_setprio 0
	ds_read_b128 v[146:149], v193 offset:0x3c00
	s_waitcnt lgkmcnt(2)
	s_setprio 1
	v_mfma_f32_16x16x32_bf16 v[44:47], v[8:11], v[130:133], v[208:211]
	v_mfma_f32_16x16x32_bf16 v[40:43], v[8:11], v[134:137], v[212:215]
	v_mfma_f32_16x16x32_bf16 v[36:39], v[8:11], v[138:141], v[216:219]
	v_mfma_f32_16x16x32_bf16 v[32:35], v[8:11], v[142:145], v[220:223]
	s_setprio 0
	s_waitcnt lgkmcnt(1)
	s_setprio 1
	v_mfma_f32_16x16x32_bf16 v[28:31], v[12:15], v[130:133], v[224:227]
	v_mfma_f32_16x16x32_bf16 v[24:27], v[12:15], v[134:137], v[228:231]
	v_mfma_f32_16x16x32_bf16 v[20:23], v[12:15], v[138:141], v[232:235]
	v_mfma_f32_16x16x32_bf16 v[16:19], v[12:15], v[142:145], v[236:239]
	s_setprio 0
	s_waitcnt lgkmcnt(0)
	s_setprio 1
	v_mfma_f32_16x16x32_bf16 v[12:15], v[146:149], v[130:133], v[0:3]
	v_mfma_f32_16x16x32_bf16 v[8:11], v[146:149], v[134:137], v[4:7]
	v_mfma_f32_16x16x32_bf16 v[4:7], v[146:149], v[138:141], v[240:243]
	v_mfma_f32_16x16x32_bf16 v[0:3], v[146:149], v[142:145], v[244:247]
	s_setprio 0
	s_waitcnt vmcnt(0)
	s_and_saveexec_b64 s[28:29], s[0:1]
	v_fmamk_f32 v128, v128, 0x3a800000, v183
	s_nop 0
	v_rsq_f32_e32 v128, v128
	s_nop 0
	ds_write_b32 v195, v128
	s_or_b64 exec, exec, s[28:29]
	s_add_u32 s17, s42, s26
	s_addc_u32 s19, s43, s27
	s_add_u32 s30, s44, s2
	s_addc_u32 s31, s45, s3
	s_mov_b32 s34, -15
	s_waitcnt vmcnt(0) lgkmcnt(0)
	s_barrier
	v_or_b32_e32 v209, 0x10000, v194
	v_add_u32_e32 v207, 0x10000, v193
	ds_read_b128 v[212:215], v209 offset:0
	ds_read_b128 v[216:219], v209 offset:2048
	ds_read_b128 v[220:223], v209 offset:4096
	ds_read_b128 v[224:227], v209 offset:6144
	ds_read_b128 v[228:231], v207 offset:0
	ds_read_b128 v[168:171], v207 offset:2048
	ds_read_b128 v[160:163], v207 offset:4096
	v_readfirstlane_b32 s35, v175
	v_lshlrev_b32_e32 v232, 1, v176
	v_lshlrev_b32_e32 v233, 1, v178
	v_lshlrev_b32_e32 v234, 1, v180
	v_lshlrev_b32_e32 v235, 1, v191
	s_cmp_lg_u32 s34, -1
	s_cselect_b32 s28, s30, s22
	s_cselect_b32 s29, s31, s23
	s_cselect_b32 s26, s17, s24
	s_cselect_b32 s27, s19, s25
	s_cselect_b64 vcc, -1, s[20:21]
	v_readfirstlane_b32 s36, v175
	s_nop 3
	s_lshr_b32 s36, s36, 12
	s_cmp_eq_u32 s36, 1
	s_cbranch_scc1 .Lwib_head

; template <int EPI>
; __device__ __forceinline__ void gemm_phase(const Params& p, const u16* __restrict__ A, const u16* __restrict__ Bt, int K, int nN,
;                            u16* __restrict__ Cout, int ldc) {
;     ...
;       GSTEP(0, 2); GSTEP(1, 6); GSTEP(2, 6); GSTEP(3, 6); GSTEP(4, 2); GSTEP(5, 2); GSTEP(6, 2); GSTEP(7, 2);
;       GSTEP(8, 2); GSTEP(9, 2); GSTEP(10, 2); GSTEP(11, 2); GSTEP(12, 2); GSTEP(13, 2); GSTEP(14, 1); GSTEP(15, 0);
.Lwib_head:
	s_waitcnt lgkmcnt(2)
	s_setprio 2
	v_mfma_f32_16x16x32_bf16 v[124:127], v[228:231], v[212:215], v[124:127]
	v_mfma_f32_16x16x32_bf16 v[120:123], v[228:231], v[216:219], v[120:123]
	v_mfma_f32_16x16x32_bf16 v[116:119], v[228:231], v[220:223], v[116:119]
	v_mfma_f32_16x16x32_bf16 v[112:115], v[228:231], v[224:227], v[112:115]
	s_setprio 1
	s_cbranch_vccz .Lwib_sk21
	s_mov_b32 m0, s35
	s_nop 0
	global_load_lds_dwordx4 v232, s[28:29]
	s_add_u32 m0, s35, 0x2000
	s_nop 0
	global_load_lds_dwordx4 v233, s[28:29]
.Lwib_sk21:
	ds_read_b128 v[164:167], v207 offset:6144
	ds_read_b128 v[128:131], v209 offset:1024
	ds_read_b128 v[132:135], v209 offset:3072
	ds_read_b128 v[136:139], v209 offset:5120
	ds_read_b128 v[140:143], v209 offset:7168
	s_waitcnt lgkmcnt(6)
	s_setprio 2
	v_mfma_f32_16x16x32_bf16 v[108:111], v[168:171], v[212:215], v[108:111]
	v_mfma_f32_16x16x32_bf16 v[104:107], v[168:171], v[216:219], v[104:107]
	v_mfma_f32_16x16x32_bf16 v[100:103], v[168:171], v[220:223], v[100:103]
	v_mfma_f32_16x16x32_bf16 v[96:99], v[168:171], v[224:227], v[96:99]
	s_setprio 1
	s_cbranch_vccz .Lwib_sk22
	s_add_u32 m0, s35, 0x4000
	s_nop 0
	global_load_lds_dwordx4 v234, s[28:29]
	s_add_u32 m0, s35, 0x6000
	s_nop 0
	global_load_lds_dwordx4 v235, s[28:29]
.Lwib_sk22:
	ds_read_b128 v[168:171], v207 offset:8192
	s_waitcnt lgkmcnt(6)
	s_setprio 2
	v_mfma_f32_16x16x32_bf16 v[92:95], v[160:163], v[212:215], v[92:95]
	v_mfma_f32_16x16x32_bf16 v[88:91], v[160:163], v[216:219], v[88:91]
	v_mfma_f32_16x16x32_bf16 v[84:87], v[160:163], v[220:223], v[84:87]
	v_mfma_f32_16x16x32_bf16 v[80:83], v[160:163], v[224:227], v[80:83]
	s_setprio 1
	s_cbranch_vccz .Lwib_sk23
	s_add_u32 m0, s35, 0x8000
	s_nop 0
	global_load_lds_dwordx4 v232, s[26:27]
	s_add_u32 m0, s35, 0xa000
	s_nop 0
	global_load_lds_dwordx4 v233, s[26:27]
.Lwib_sk23:
	ds_read_b128 v[160:163], v207 offset:10240
	s_waitcnt lgkmcnt(6)
	s_setprio 2
	v_mfma_f32_16x16x32_bf16 v[76:79], v[164:167], v[212:215], v[76:79]
	v_mfma_f32_16x16x32_bf16 v[72:75], v[164:167], v[216:219], v[72:75]
	v_mfma_f32_16x16x32_bf16 v[68:71], v[164:167], v[220:223], v[68:71]
	v_mfma_f32_16x16x32_bf16 v[64:67], v[164:167], v[224:227], v[64:67]
	s_setprio 1
	s_cbranch_vccz .Lwib_sk24
	s_add_u32 m0, s35, 0xc000
	s_nop 0
	global_load_lds_dwordx4 v234, s[26:27]
	s_add_u32 m0, s35, 0xe000
	s_nop 0
	global_load_lds_dwordx4 v235, s[26:27]
; __device__ __forceinline__ float rsq_(float x) { return __builtin_amdgcn_rsqf(x); }
; #define WAIT_V(n) asm volatile("s_waitcnt vmcnt(%0)" ::"n"(n) : "memory")
; template <int EPI>
; __device__ __forceinline__ void gemm_phase(const Params& p, const u16* __restrict__ A, const u16* __restrict__ Bt, int K, int nN,
;                            u16* __restrict__ Cout, int ldc) {
;     ...
;       GSTEP(0, 2); GSTEP(1, 6); GSTEP(2, 6); GSTEP(3, 6); GSTEP(4, 2); GSTEP(5, 2); GSTEP(6, 2); GSTEP(7, 2);
;       GSTEP(8, 2); GSTEP(9, 2); GSTEP(10, 2); GSTEP(11, 2); GSTEP(12, 2); GSTEP(13, 2); GSTEP(14, 1); GSTEP(15, 0);
;       WAIT_V(0);
;       if (EPI != EPI_SS && t == 0 && tid < 256) rsl[tid] = rsq_(ssv * (1.f / DM) + EPS);
;       __syncthreads();
;     }
.Lwib_sk24:
	ds_read_b128 v[164:167], v207 offset:12288
	s_waitcnt lgkmcnt(2)
	s_setprio 2
	v_mfma_f32_16x16x32_bf16 v[60:63], v[168:171], v[212:215], v[60:63]
	v_mfma_f32_16x16x32_bf16 v[56:59], v[168:171], v[216:219], v[56:59]
	v_mfma_f32_16x16x32_bf16 v[52:55], v[168:171], v[220:223], v[52:55]
	v_mfma_f32_16x16x32_bf16 v[48:51], v[168:171], v[224:227], v[48:51]
	s_setprio 1
	ds_read_b128 v[168:171], v207 offset:14336
	s_waitcnt lgkmcnt(2)
	s_setprio 2
	v_mfma_f32_16x16x32_bf16 v[44:47], v[160:163], v[212:215], v[44:47]
	v_mfma_f32_16x16x32_bf16 v[40:43], v[160:163], v[216:219], v[40:43]
	v_mfma_f32_16x16x32_bf16 v[36:39], v[160:163], v[220:223], v[36:39]
	v_mfma_f32_16x16x32_bf16 v[32:35], v[160:163], v[224:227], v[32:35]
	s_setprio 1
	ds_read_b128 v[160:163], v207 offset:1024
	s_waitcnt lgkmcnt(2)
	s_setprio 2
	v_mfma_f32_16x16x32_bf16 v[28:31], v[164:167], v[212:215], v[28:31]
	v_mfma_f32_16x16x32_bf16 v[24:27], v[164:167], v[216:219], v[24:27]
	v_mfma_f32_16x16x32_bf16 v[20:23], v[164:167], v[220:223], v[20:23]
	v_mfma_f32_16x16x32_bf16 v[16:19], v[164:167], v[224:227], v[16:19]
	s_setprio 1
	ds_read_b128 v[164:167], v207 offset:3072
	s_waitcnt lgkmcnt(2)
	s_setprio 2
	v_mfma_f32_16x16x32_bf16 v[12:15], v[168:171], v[212:215], v[12:15]
	v_mfma_f32_16x16x32_bf16 v[8:11], v[168:171], v[216:219], v[8:11]
	v_mfma_f32_16x16x32_bf16 v[4:7], v[168:171], v[220:223], v[4:7]
	v_mfma_f32_16x16x32_bf16 v[0:3], v[168:171], v[224:227], v[0:3]
	s_setprio 1
	ds_read_b128 v[144:147], v207 offset:5120
	s_waitcnt lgkmcnt(2)
	s_setprio 2
	v_mfma_f32_16x16x32_bf16 v[124:127], v[160:163], v[128:131], v[124:127]
	v_mfma_f32_16x16x32_bf16 v[120:123], v[160:163], v[132:135], v[120:123]
	v_mfma_f32_16x16x32_bf16 v[116:119], v[160:163], v[136:139], v[116:119]
	v_mfma_f32_16x16x32_bf16 v[112:115], v[160:163], v[140:143], v[112:115]
	s_setprio 1
	ds_read_b128 v[148:151], v207 offset:7168
	s_waitcnt lgkmcnt(2)
	s_setprio 2
	v_mfma_f32_16x16x32_bf16 v[108:111], v[164:167], v[128:131], v[108:111]
	v_mfma_f32_16x16x32_bf16 v[104:107], v[164:167], v[132:135], v[104:107]
	v_mfma_f32_16x16x32_bf16 v[100:103], v[164:167], v[136:139], v[100:103]
	v_mfma_f32_16x16x32_bf16 v[96:99], v[164:167], v[140:143], v[96:99]
	s_setprio 1
	ds_read_b128 v[152:155], v207 offset:9216
	s_waitcnt lgkmcnt(2)
	s_setprio 2
	v_mfma_f32_16x16x32_bf16 v[92:95], v[144:147], v[128:131], v[92:95]
	v_mfma_f32_16x16x32_bf16 v[88:91], v[144:147], v[132:135], v[88:91]
	v_mfma_f32_16x16x32_bf16 v[84:87], v[144:147], v[136:139], v[84:87]
	v_mfma_f32_16x16x32_bf16 v[80:83], v[144:147], v[140:143], v[80:83]
	s_setprio 1
	ds_read_b128 v[144:147], v207 offset:11264
	s_waitcnt lgkmcnt(2)
	s_setprio 2
	v_mfma_f32_16x16x32_bf16 v[76:79], v[148:151], v[128:131], v[76:79]
	v_mfma_f32_16x16x32_bf16 v[72:75], v[148:151], v[132:135], v[72:75]
	v_mfma_f32_16x16x32_bf16 v[68:71], v[148:151], v[136:139], v[68:71]
	v_mfma_f32_16x16x32_bf16 v[64:67], v[148:151], v[140:143], v[64:67]
	s_setprio 1
	ds_read_b128 v[148:151], v207 offset:13312
	s_waitcnt lgkmcnt(2)
	s_setprio 2
	v_mfma_f32_16x16x32_bf16 v[60:63], v[152:155], v[128:131], v[60:63]
	v_mfma_f32_16x16x32_bf16 v[56:59], v[152:155], v[132:135], v[56:59]
	v_mfma_f32_16x16x32_bf16 v[52:55], v[152:155], v[136:139], v[52:55]
	v_mfma_f32_16x16x32_bf16 v[48:51], v[152:155], v[140:143], v[48:51]
	s_setprio 1
	ds_read_b128 v[152:155], v207 offset:15360
	s_waitcnt lgkmcnt(2)
	s_setprio 2
	v_mfma_f32_16x16x32_bf16 v[44:47], v[144:147], v[128:131], v[44:47]
	v_mfma_f32_16x16x32_bf16 v[40:43], v[144:147], v[132:135], v[40:43]
	v_mfma_f32_16x16x32_bf16 v[36:39], v[144:147], v[136:139], v[36:39]
	v_mfma_f32_16x16x32_bf16 v[32:35], v[144:147], v[140:143], v[32:35]
	s_setprio 1
	s_waitcnt vmcnt(0) lgkmcnt(0)
	s_barrier
	v_xor_b32_e32 v209, 0x10000, v209
	v_xor_b32_e32 v207, 0x10000, v207
	ds_read_b128 v[212:215], v209 offset:0
	ds_read_b128 v[216:219], v209 offset:2048
	ds_read_b128 v[220:223], v209 offset:4096
	ds_read_b128 v[224:227], v209 offset:6144
	ds_read_b128 v[228:231], v207 offset:0
	ds_read_b128 v[168:171], v207 offset:2048
	ds_read_b128 v[160:163], v207 offset:4096
	s_add_u32 s30, s30, 0x80
	s_addc_u32 s31, s31, 0
	s_add_u32 s17, s17, 0x80
	s_addc_u32 s19, s19, 0
	s_xor_b32 s35, s35, 0x10000
	s_add_i32 s34, s34, 1
	s_cmp_lg_u32 s34, -1
	s_cselect_b32 s28, s30, s22
	s_cselect_b32 s29, s31, s23
	s_cselect_b32 s26, s17, s24
	s_cselect_b32 s27, s19, s25
	s_cselect_b64 vcc, -1, s[20:21]
	s_cmp_eq_u32 s34, 0
	s_cselect_b64 vcc, 0, vcc
	s_setprio 2
	v_mfma_f32_16x16x32_bf16 v[28:31], v[148:151], v[128:131], v[28:31]
	v_mfma_f32_16x16x32_bf16 v[24:27], v[148:151], v[132:135], v[24:27]
	v_mfma_f32_16x16x32_bf16 v[20:23], v[148:151], v[136:139], v[20:23]
	v_mfma_f32_16x16x32_bf16 v[16:19], v[148:151], v[140:143], v[16:19]
	s_setprio 1
	s_setprio 2
	v_mfma_f32_16x16x32_bf16 v[12:15], v[152:155], v[128:131], v[12:15]
	v_mfma_f32_16x16x32_bf16 v[8:11], v[152:155], v[132:135], v[8:11]
	v_mfma_f32_16x16x32_bf16 v[4:7], v[152:155], v[136:139], v[4:7]
	v_mfma_f32_16x16x32_bf16 v[0:3], v[152:155], v[140:143], v[0:3]
	s_setprio 1
	s_cmp_lg_u32 s34, 0
	s_cbranch_scc1 .Lwib_head
	s_waitcnt lgkmcnt(0)
	s_setprio 0
	s_branch .LBB0_854

; #define WAIT_V(n) asm volatile("s_waitcnt vmcnt(%0)" ::"n"(n) : "memory")
; #define DSR(dst, addr, OFF) asm volatile("ds_read_b128 %0, %1 offset:%2" : "=&v"(dst) : "v"(addr), "i"(OFF) : "memory")
; template <int EPI>
; __device__ __forceinline__ void gemm_phase(const Params& p, const u16* __restrict__ A, const u16* __restrict__ Bt, int K, int nN,
;                            u16* __restrict__ Cout, int ldc) {
;     ...
;     f32x4 acc[8][4];
; #pragma unroll
;     for (int m = 0; m < 8; ++m)
; #pragma unroll
;       for (int n = 0; n < 4; ++n) acc[m][n] = f32x4{0.f, 0.f, 0.f, 0.f};
;     if (!prefetched) {
; #pragma unroll
;       for (int i = 0; i < 8; ++i) GLDS_PIECE(i, Ab, Bb, 0);
;       WAIT_V(0); __syncthreads();
;     }
;     prefetched = has_next;
;     for (int t = 0; t < nt; ++t) {
;       const int cur = t & 1, nb = cur ^ 1;
;       const bool last = (t + 1 == nt);
;       const bool dostage = !last || has_next;
;       const u16* pa = last ? Abn : Ab + (t + 1) * BK;
;       const u16* pb = last ? Bbn : Bb + (t + 1) * BK;
;       bf16x8 Ar[3], Bq[2][4];
;       const unsigned la_u = lds0 + (unsigned)(cur * STAGE_B + aoff), lb_u = lds0 + (unsigned)(cur * STAGE_B + boff);
;     ...
;       DSR(Bq[0][0], lb_u, 0); DSR(Bq[0][1], lb_u, 2048); DSR(Bq[0][2], lb_u, 4096); DSR(Bq[0][3], lb_u, 6144);
;       DSR(Ar[0], la_u, 0); DSR(Ar[1], la_u, 2048);
;     ...
;       GSTEP(0, 2); GSTEP(1, 6); GSTEP(2, 6); GSTEP(3, 6); GSTEP(4, 2); GSTEP(5, 2); GSTEP(6, 2); GSTEP(7, 2);
;       GSTEP(8, 2); GSTEP(9, 2); GSTEP(10, 2); GSTEP(11, 2); GSTEP(12, 2); GSTEP(13, 2); GSTEP(14, 1); GSTEP(15, 0);
.LBB0_1104:
	s_mul_i32 s1, s24, s28
	s_mul_hi_i32 s0, s24, s28
	s_add_u32 s14, s22, s1
	s_addc_u32 s15, s23, s0
	s_mul_i32 s1, s24, s27
	s_mul_hi_i32 s0, s24, s27
	s_add_u32 s16, s25, s1
	v_mov_b32_e32 v0, 0
	s_addc_u32 s17, s26, s0
	s_mov_b32 s29, 0
	s_mov_b64 s[0:1], 0
	s_mov_b32 s30, 0
	v_mov_b32_e32 v1, v0
	v_mov_b32_e32 v2, v0
	v_mov_b32_e32 v3, v0
	v_mov_b32_e32 v4, v0
	v_mov_b32_e32 v5, v0
	v_mov_b32_e32 v6, v0
	v_mov_b32_e32 v7, v0
	v_mov_b32_e32 v8, v0
	v_mov_b32_e32 v9, v0
	v_mov_b32_e32 v10, v0
	v_mov_b32_e32 v11, v0
	v_mov_b32_e32 v12, v0
	v_mov_b32_e32 v13, v0
	v_mov_b32_e32 v14, v0
	v_mov_b32_e32 v15, v0
	v_mov_b32_e32 v16, v0
	v_mov_b32_e32 v17, v0
	v_mov_b32_e32 v18, v0
	v_mov_b32_e32 v19, v0
	v_mov_b32_e32 v20, v0
	v_mov_b32_e32 v21, v0
	v_mov_b32_e32 v22, v0
	v_mov_b32_e32 v23, v0
	v_mov_b32_e32 v24, v0
	v_mov_b32_e32 v25, v0
	v_mov_b32_e32 v26, v0
	v_mov_b32_e32 v27, v0
	v_mov_b32_e32 v28, v0
	v_mov_b32_e32 v29, v0
	v_mov_b32_e32 v30, v0
	v_mov_b32_e32 v31, v0
	v_mov_b32_e32 v32, v0
	v_mov_b32_e32 v33, v0
	v_mov_b32_e32 v34, v0
	v_mov_b32_e32 v35, v0
	v_mov_b32_e32 v36, v0
	v_mov_b32_e32 v37, v0
	v_mov_b32_e32 v38, v0
	v_mov_b32_e32 v39, v0
	v_mov_b32_e32 v40, v0
	v_mov_b32_e32 v41, v0
	v_mov_b32_e32 v42, v0
	v_mov_b32_e32 v43, v0
	v_mov_b32_e32 v44, v0
	v_mov_b32_e32 v45, v0
	v_mov_b32_e32 v46, v0
	v_mov_b32_e32 v47, v0
	v_mov_b32_e32 v48, v0
	v_mov_b32_e32 v49, v0
	v_mov_b32_e32 v50, v0
	v_mov_b32_e32 v51, v0
	v_mov_b32_e32 v52, v0
	v_mov_b32_e32 v53, v0
	v_mov_b32_e32 v54, v0
	v_mov_b32_e32 v55, v0
	v_mov_b32_e32 v56, v0
	v_mov_b32_e32 v57, v0
	v_mov_b32_e32 v58, v0
	v_mov_b32_e32 v59, v0
	v_mov_b32_e32 v60, v0
	v_mov_b32_e32 v61, v0
	v_mov_b32_e32 v62, v0
	v_mov_b32_e32 v63, v0
	v_mov_b32_e32 v64, v0
	v_mov_b32_e32 v65, v0
	v_mov_b32_e32 v66, v0
	v_mov_b32_e32 v67, v0
	v_mov_b32_e32 v68, v0
	v_mov_b32_e32 v69, v0
	v_mov_b32_e32 v70, v0
	v_mov_b32_e32 v71, v0
	v_mov_b32_e32 v72, v0
	v_mov_b32_e32 v73, v0
	v_mov_b32_e32 v74, v0
	v_mov_b32_e32 v75, v0
	v_mov_b32_e32 v76, v0
	v_mov_b32_e32 v77, v0
	v_mov_b32_e32 v78, v0
	v_mov_b32_e32 v79, v0
	v_mov_b32_e32 v80, v0
	v_mov_b32_e32 v81, v0
	v_mov_b32_e32 v82, v0
	v_mov_b32_e32 v83, v0
	v_mov_b32_e32 v84, v0
	v_mov_b32_e32 v85, v0
	v_mov_b32_e32 v86, v0
	v_mov_b32_e32 v87, v0
	v_mov_b32_e32 v88, v0
	v_mov_b32_e32 v89, v0
	v_mov_b32_e32 v90, v0
	v_mov_b32_e32 v91, v0
	v_mov_b32_e32 v92, v0
	v_mov_b32_e32 v93, v0
	v_mov_b32_e32 v94, v0
	v_mov_b32_e32 v95, v0
	v_mov_b32_e32 v96, v0
	v_mov_b32_e32 v97, v0
	v_mov_b32_e32 v98, v0
	v_mov_b32_e32 v99, v0
	v_mov_b32_e32 v100, v0
	v_mov_b32_e32 v101, v0
	v_mov_b32_e32 v102, v0
	v_mov_b32_e32 v103, v0
	v_mov_b32_e32 v104, v0
	v_mov_b32_e32 v105, v0
	v_mov_b32_e32 v106, v0
	v_mov_b32_e32 v107, v0
	v_mov_b32_e32 v108, v0
	v_mov_b32_e32 v109, v0
	v_mov_b32_e32 v110, v0
	v_mov_b32_e32 v111, v0
	v_mov_b32_e32 v112, v0
	v_mov_b32_e32 v113, v0
	v_mov_b32_e32 v114, v0
	v_mov_b32_e32 v115, v0
	v_mov_b32_e32 v116, v0
	v_mov_b32_e32 v117, v0
	v_mov_b32_e32 v118, v0
	v_mov_b32_e32 v119, v0
	v_mov_b32_e32 v120, v0
	v_mov_b32_e32 v121, v0
	v_mov_b32_e32 v122, v0
	v_mov_b32_e32 v123, v0
	v_mov_b32_e32 v124, v0
	v_mov_b32_e32 v125, v0
	v_mov_b32_e32 v126, v0
	v_mov_b32_e32 v127, v0
	s_not_b32 s30, s21
	s_mov_b64 s[34:35], s[16:17]
	s_mov_b64 s[0:1], s[14:15]
	v_mov_b32_e32 v198, v194
	v_mov_b32_e32 v197, v193
	ds_read_b128 v[212:215], v198 offset:0
	ds_read_b128 v[216:219], v198 offset:2048
	ds_read_b128 v[220:223], v198 offset:4096
	ds_read_b128 v[224:227], v198 offset:6144
	ds_read_b128 v[228:231], v197 offset:0
	ds_read_b128 v[168:171], v197 offset:2048
	ds_read_b128 v[160:163], v197 offset:4096
	v_readfirstlane_b32 s29, v192
	s_add_u32 s29, s29, 0x10000
	v_lshlrev_b32_e32 v232, 1, v174
	v_lshlrev_b32_e32 v233, 1, v176
	v_lshlrev_b32_e32 v234, 1, v178
	v_lshlrev_b32_e32 v235, 1, v180
	s_cmp_lg_u32 s30, -1
	s_cselect_b32 s34, s34, s10
	s_cselect_b32 s35, s35, s11
	s_cselect_b32 s0, s0, s6
	s_cselect_b32 s1, s1, s7
	s_cselect_b64 vcc, -1, s[12:13]
	v_readfirstlane_b32 s31, v192
	s_nop 3
	s_lshr_b32 s31, s31, 12
	s_cmp_eq_u32 s31, 1
	s_cbranch_scc1 .Lssb_head

; template <int EPI>
; __device__ __forceinline__ void gemm_phase(const Params& p, const u16* __restrict__ A, const u16* __restrict__ Bt, int K, int nN,
;                            u16* __restrict__ Cout, int ldc) {
;     ...
;       GSTEP(0, 2); GSTEP(1, 6); GSTEP(2, 6); GSTEP(3, 6); GSTEP(4, 2); GSTEP(5, 2); GSTEP(6, 2); GSTEP(7, 2);
;       GSTEP(8, 2); GSTEP(9, 2); GSTEP(10, 2); GSTEP(11, 2); GSTEP(12, 2); GSTEP(13, 2); GSTEP(14, 1); GSTEP(15, 0);
.Lssb_head:
	s_waitcnt lgkmcnt(2)
	s_setprio 2
	v_mfma_f32_16x16x32_bf16 v[124:127], v[228:231], v[212:215], v[124:127]
	v_mfma_f32_16x16x32_bf16 v[120:123], v[228:231], v[216:219], v[120:123]
	v_mfma_f32_16x16x32_bf16 v[116:119], v[228:231], v[220:223], v[116:119]
	v_mfma_f32_16x16x32_bf16 v[112:115], v[228:231], v[224:227], v[112:115]
	s_setprio 1
	s_cbranch_vccz .Lssb_sk5
	s_mov_b32 m0, s29
	s_nop 0
	global_load_lds_dwordx4 v232, s[34:35]
	s_add_u32 m0, s29, 0x2000
	s_nop 0
	global_load_lds_dwordx4 v233, s[34:35]
.Lssb_sk5:
	ds_read_b128 v[164:167], v197 offset:6144
	ds_read_b128 v[128:131], v198 offset:1024
	ds_read_b128 v[132:135], v198 offset:3072
	ds_read_b128 v[136:139], v198 offset:5120
	ds_read_b128 v[140:143], v198 offset:7168
	s_waitcnt lgkmcnt(6)
	s_setprio 2
	v_mfma_f32_16x16x32_bf16 v[108:111], v[168:171], v[212:215], v[108:111]
	v_mfma_f32_16x16x32_bf16 v[104:107], v[168:171], v[216:219], v[104:107]
	v_mfma_f32_16x16x32_bf16 v[100:103], v[168:171], v[220:223], v[100:103]
	v_mfma_f32_16x16x32_bf16 v[96:99], v[168:171], v[224:227], v[96:99]
	s_setprio 1
	s_cbranch_vccz .Lssb_sk6
	s_add_u32 m0, s29, 0x4000
	s_nop 0
	global_load_lds_dwordx4 v234, s[34:35]
	s_add_u32 m0, s29, 0x6000
	s_nop 0
	global_load_lds_dwordx4 v235, s[34:35]
.Lssb_sk6:
	ds_read_b128 v[168:171], v197 offset:8192
	s_waitcnt lgkmcnt(6)
	s_setprio 2
	v_mfma_f32_16x16x32_bf16 v[92:95], v[160:163], v[212:215], v[92:95]
	v_mfma_f32_16x16x32_bf16 v[88:91], v[160:163], v[216:219], v[88:91]
	v_mfma_f32_16x16x32_bf16 v[84:87], v[160:163], v[220:223], v[84:87]
	v_mfma_f32_16x16x32_bf16 v[80:83], v[160:163], v[224:227], v[80:83]
	s_setprio 1
	s_cbranch_vccz .Lssb_sk7
	s_add_u32 m0, s29, 0x8000
	s_nop 0
	global_load_lds_dwordx4 v232, s[0:1]
	s_add_u32 m0, s29, 0xa000
	s_nop 0
	global_load_lds_dwordx4 v233, s[0:1]
.Lssb_sk7:
	ds_read_b128 v[160:163], v197 offset:10240
	s_waitcnt lgkmcnt(6)
	s_setprio 2
	v_mfma_f32_16x16x32_bf16 v[76:79], v[164:167], v[212:215], v[76:79]
	v_mfma_f32_16x16x32_bf16 v[72:75], v[164:167], v[216:219], v[72:75]
	v_mfma_f32_16x16x32_bf16 v[68:71], v[164:167], v[220:223], v[68:71]
	v_mfma_f32_16x16x32_bf16 v[64:67], v[164:167], v[224:227], v[64:67]
	s_setprio 1
	s_cbranch_vccz .Lssb_sk8
	s_add_u32 m0, s29, 0xc000
	s_nop 0
	global_load_lds_dwordx4 v234, s[0:1]
	s_add_u32 m0, s29, 0xe000
	s_nop 0
	global_load_lds_dwordx4 v235, s[0:1]
; __device__ __forceinline__ float rsq_(float x) { return __builtin_amdgcn_rsqf(x); }
; #define WAIT_V(n) asm volatile("s_waitcnt vmcnt(%0)" ::"n"(n) : "memory")
; template <int EPI>
; __device__ __forceinline__ void gemm_phase(const Params& p, const u16* __restrict__ A, const u16* __restrict__ Bt, int K, int nN,
;                            u16* __restrict__ Cout, int ldc) {
;     ...
;       GSTEP(0, 2); GSTEP(1, 6); GSTEP(2, 6); GSTEP(3, 6); GSTEP(4, 2); GSTEP(5, 2); GSTEP(6, 2); GSTEP(7, 2);
;       GSTEP(8, 2); GSTEP(9, 2); GSTEP(10, 2); GSTEP(11, 2); GSTEP(12, 2); GSTEP(13, 2); GSTEP(14, 1); GSTEP(15, 0);
;       WAIT_V(0);
;       if (EPI != EPI_SS && t == 0 && tid < 256) rsl[tid] = rsq_(ssv * (1.f / DM) + EPS);
;       __syncthreads();
;     }
.Lssb_sk8:
	ds_read_b128 v[164:167], v197 offset:12288
	s_waitcnt lgkmcnt(2)
	s_setprio 2
	v_mfma_f32_16x16x32_bf16 v[60:63], v[168:171], v[212:215], v[60:63]
	v_mfma_f32_16x16x32_bf16 v[56:59], v[168:171], v[216:219], v[56:59]
	v_mfma_f32_16x16x32_bf16 v[52:55], v[168:171], v[220:223], v[52:55]
	v_mfma_f32_16x16x32_bf16 v[48:51], v[168:171], v[224:227], v[48:51]
	s_setprio 1
	ds_read_b128 v[168:171], v197 offset:14336
	s_waitcnt lgkmcnt(2)
	s_setprio 2
	v_mfma_f32_16x16x32_bf16 v[44:47], v[160:163], v[212:215], v[44:47]
	v_mfma_f32_16x16x32_bf16 v[40:43], v[160:163], v[216:219], v[40:43]
	v_mfma_f32_16x16x32_bf16 v[36:39], v[160:163], v[220:223], v[36:39]
	v_mfma_f32_16x16x32_bf16 v[32:35], v[160:163], v[224:227], v[32:35]
	s_setprio 1
	ds_read_b128 v[160:163], v197 offset:1024
	s_waitcnt lgkmcnt(2)
	s_setprio 2
	v_mfma_f32_16x16x32_bf16 v[28:31], v[164:167], v[212:215], v[28:31]
	v_mfma_f32_16x16x32_bf16 v[24:27], v[164:167], v[216:219], v[24:27]
	v_mfma_f32_16x16x32_bf16 v[20:23], v[164:167], v[220:223], v[20:23]
	v_mfma_f32_16x16x32_bf16 v[16:19], v[164:167], v[224:227], v[16:19]
	s_setprio 1
	ds_read_b128 v[164:167], v197 offset:3072
	s_waitcnt lgkmcnt(2)
	s_setprio 2
	v_mfma_f32_16x16x32_bf16 v[12:15], v[168:171], v[212:215], v[12:15]
	v_mfma_f32_16x16x32_bf16 v[8:11], v[168:171], v[216:219], v[8:11]
	v_mfma_f32_16x16x32_bf16 v[4:7], v[168:171], v[220:223], v[4:7]
	v_mfma_f32_16x16x32_bf16 v[0:3], v[168:171], v[224:227], v[0:3]
	s_setprio 1
	ds_read_b128 v[144:147], v197 offset:5120
	s_waitcnt lgkmcnt(2)
	s_setprio 2
	v_mfma_f32_16x16x32_bf16 v[124:127], v[160:163], v[128:131], v[124:127]
	v_mfma_f32_16x16x32_bf16 v[120:123], v[160:163], v[132:135], v[120:123]
	v_mfma_f32_16x16x32_bf16 v[116:119], v[160:163], v[136:139], v[116:119]
	v_mfma_f32_16x16x32_bf16 v[112:115], v[160:163], v[140:143], v[112:115]
	s_setprio 1
	ds_read_b128 v[148:151], v197 offset:7168
	s_waitcnt lgkmcnt(2)
	s_setprio 2
	v_mfma_f32_16x16x32_bf16 v[108:111], v[164:167], v[128:131], v[108:111]
	v_mfma_f32_16x16x32_bf16 v[104:107], v[164:167], v[132:135], v[104:107]
	v_mfma_f32_16x16x32_bf16 v[100:103], v[164:167], v[136:139], v[100:103]
	v_mfma_f32_16x16x32_bf16 v[96:99], v[164:167], v[140:143], v[96:99]
	s_setprio 1
	ds_read_b128 v[152:155], v197 offset:9216
	s_waitcnt lgkmcnt(2)
	s_setprio 2
	v_mfma_f32_16x16x32_bf16 v[92:95], v[144:147], v[128:131], v[92:95]
	v_mfma_f32_16x16x32_bf16 v[88:91], v[144:147], v[132:135], v[88:91]
	v_mfma_f32_16x16x32_bf16 v[84:87], v[144:147], v[136:139], v[84:87]
	v_mfma_f32_16x16x32_bf16 v[80:83], v[144:147], v[140:143], v[80:83]
	s_setprio 1
	ds_read_b128 v[144:147], v197 offset:11264
	s_waitcnt lgkmcnt(2)
	s_setprio 2
	v_mfma_f32_16x16x32_bf16 v[76:79], v[148:151], v[128:131], v[76:79]
	v_mfma_f32_16x16x32_bf16 v[72:75], v[148:151], v[132:135], v[72:75]
	v_mfma_f32_16x16x32_bf16 v[68:71], v[148:151], v[136:139], v[68:71]
	v_mfma_f32_16x16x32_bf16 v[64:67], v[148:151], v[140:143], v[64:67]
	s_setprio 1
	ds_read_b128 v[148:151], v197 offset:13312
	s_waitcnt lgkmcnt(2)
	s_setprio 2
	v_mfma_f32_16x16x32_bf16 v[60:63], v[152:155], v[128:131], v[60:63]
	v_mfma_f32_16x16x32_bf16 v[56:59], v[152:155], v[132:135], v[56:59]
	v_mfma_f32_16x16x32_bf16 v[52:55], v[152:155], v[136:139], v[52:55]
	v_mfma_f32_16x16x32_bf16 v[48:51], v[152:155], v[140:143], v[48:51]
	s_setprio 1
	ds_read_b128 v[152:155], v197 offset:15360
	s_waitcnt lgkmcnt(2)
	s_setprio 2
	v_mfma_f32_16x16x32_bf16 v[44:47], v[144:147], v[128:131], v[44:47]
	v_mfma_f32_16x16x32_bf16 v[40:43], v[144:147], v[132:135], v[40:43]
	v_mfma_f32_16x16x32_bf16 v[36:39], v[144:147], v[136:139], v[36:39]
	v_mfma_f32_16x16x32_bf16 v[32:35], v[144:147], v[140:143], v[32:35]
	s_setprio 1
	s_waitcnt vmcnt(0) lgkmcnt(0)
	s_barrier
	v_xor_b32_e32 v198, 0x10000, v198
	v_xor_b32_e32 v197, 0x10000, v197
	ds_read_b128 v[212:215], v198 offset:0
	ds_read_b128 v[216:219], v198 offset:2048
	ds_read_b128 v[220:223], v198 offset:4096
	ds_read_b128 v[224:227], v198 offset:6144
	ds_read_b128 v[228:231], v197 offset:0
	ds_read_b128 v[168:171], v197 offset:2048
	ds_read_b128 v[160:163], v197 offset:4096
	s_add_u32 s34, s34, 0x80
	s_addc_u32 s35, s35, 0
	s_add_u32 s0, s0, 0x80
	s_addc_u32 s1, s1, 0
	s_xor_b32 s29, s29, 0x10000
	s_add_i32 s30, s30, 1
	s_cmp_lg_u32 s30, -1
	s_cselect_b32 s34, s34, s10
	s_cselect_b32 s35, s35, s11
	s_cselect_b32 s0, s0, s6
	s_cselect_b32 s1, s1, s7
	s_cselect_b64 vcc, -1, s[12:13]
	s_cmp_eq_u32 s30, 0
	s_cselect_b64 vcc, 0, vcc
	s_setprio 2
	v_mfma_f32_16x16x32_bf16 v[28:31], v[148:151], v[128:131], v[28:31]
	v_mfma_f32_16x16x32_bf16 v[24:27], v[148:151], v[132:135], v[24:27]
	v_mfma_f32_16x16x32_bf16 v[20:23], v[148:151], v[136:139], v[20:23]
	v_mfma_f32_16x16x32_bf16 v[16:19], v[148:151], v[140:143], v[16:19]
	s_setprio 1
	s_setprio 2
	v_mfma_f32_16x16x32_bf16 v[12:15], v[152:155], v[128:131], v[12:15]
	v_mfma_f32_16x16x32_bf16 v[8:11], v[152:155], v[132:135], v[8:11]
	v_mfma_f32_16x16x32_bf16 v[4:7], v[152:155], v[136:139], v[4:7]
	v_mfma_f32_16x16x32_bf16 v[0:3], v[152:155], v[140:143], v[0:3]
	s_setprio 1
	s_cmp_lg_u32 s30, 0
	s_cbranch_scc1 .Lssb_head
	s_waitcnt lgkmcnt(0)
	s_setprio 0
	v_mov_b32_e32 v128, v124
	v_mov_b32_e32 v129, v125
	v_mov_b32_e32 v130, v126
	v_mov_b32_e32 v131, v127
	v_mov_b32_e32 v132, v120
	v_mov_b32_e32 v133, v121
	v_mov_b32_e32 v134, v122
	v_mov_b32_e32 v135, v123
	v_mov_b32_e32 v136, v116
	v_mov_b32_e32 v137, v117
	v_mov_b32_e32 v138, v118
	v_mov_b32_e32 v139, v119
	v_mov_b32_e32 v140, v112
	v_mov_b32_e32 v141, v113
	v_mov_b32_e32 v142, v114
	v_mov_b32_e32 v143, v115
	v_mov_b32_e32 v148, v64
	v_mov_b32_e32 v149, v65
	v_mov_b32_e32 v150, v66
	v_mov_b32_e32 v151, v67
	s_branch .Lss_epi

; #define DSR(dst, addr, OFF) asm volatile("ds_read_b128 %0, %1 offset:%2" : "=&v"(dst) : "v"(addr), "i"(OFF) : "memory")
; template <int EPI>
; __device__ __forceinline__ void gemm_phase(const Params& p, const u16* __restrict__ A, const u16* __restrict__ Bt, int K, int nN,
;                            u16* __restrict__ Cout, int ldc) {
;     ...
;       bf16x8 Ar[3], Bq[2][4];
;       const unsigned la_u = lds0 + (unsigned)(cur * STAGE_B + aoff), lb_u = lds0 + (unsigned)(cur * STAGE_B + boff);
;     ...
;       DSR(Bq[0][0], lb_u, 0); DSR(Bq[0][1], lb_u, 2048); DSR(Bq[0][2], lb_u, 4096); DSR(Bq[0][3], lb_u, 6144);
;       DSR(Ar[0], la_u, 0); DSR(Ar[1], la_u, 2048);
;     ...
;       GSTEP(0, 2); GSTEP(1, 6); GSTEP(2, 6); GSTEP(3, 6); GSTEP(4, 2); GSTEP(5, 2); GSTEP(6, 2); GSTEP(7, 2);
;       GSTEP(8, 2); GSTEP(9, 2); GSTEP(10, 2); GSTEP(11, 2); GSTEP(12, 2); GSTEP(13, 2); GSTEP(14, 1); GSTEP(15, 0);
.LBB0_1131:
	ds_read_b128 v[0:3], v194 offset:0
	ds_read_b128 v[4:7], v194 offset:0x800
	ds_read_b128 v[8:11], v194 offset:0x1000
	ds_read_b128 v[12:15], v194 offset:0x1800
	ds_read_b128 v[16:19], v193 offset:0
	ds_read_b128 v[20:23], v193 offset:0x800
	ds_read_b128 v[24:27], v193 offset:0x1000
	s_waitcnt lgkmcnt(2)
	s_setprio 1
	v_mfma_f32_16x16x32_bf16 v[28:31], v[16:19], v[0:3], 0
	v_mfma_f32_16x16x32_bf16 v[32:35], v[16:19], v[4:7], 0
	v_mfma_f32_16x16x32_bf16 v[36:39], v[16:19], v[8:11], 0
	v_mfma_f32_16x16x32_bf16 v[16:19], v[16:19], v[12:15], 0
	s_setprio 0
	v_mov_b32_e32 v40, v176
	v_mov_b32_e32 v41, v172
	v_lshl_add_u64 v[40:41], v[40:41], 1, s[24:25]
	v_readfirstlane_b32 s13, v198
	v_lshl_add_u64 v[40:41], v[40:41], 0, s[62:63]
	s_mov_b32 m0, s13
	s_nop 0
	global_load_lds_dwordx4 v[40:41], off
	ds_read_b128 v[40:43], v193 offset:0x1800
	ds_read_b128 v[130:133], v194 offset:0x400
	ds_read_b128 v[134:137], v194 offset:0xc00
	ds_read_b128 v[138:141], v194 offset:0x1400
	ds_read_b128 v[142:145], v194 offset:0x1c00
	s_waitcnt lgkmcnt(6)
	s_setprio 1
	v_mfma_f32_16x16x32_bf16 v[44:47], v[20:23], v[0:3], 0
	v_mfma_f32_16x16x32_bf16 v[48:51], v[20:23], v[4:7], 0
	v_mfma_f32_16x16x32_bf16 v[52:55], v[20:23], v[8:11], 0
	v_mfma_f32_16x16x32_bf16 v[20:23], v[20:23], v[12:15], 0
	s_setprio 0
	v_mov_b32_e32 v56, v178
	v_mov_b32_e32 v57, v172
	v_lshl_add_u64 v[56:57], v[56:57], 1, s[24:25]
	v_readfirstlane_b32 s13, v199
	v_lshl_add_u64 v[56:57], v[56:57], 0, s[62:63]
	s_mov_b32 m0, s13
	s_nop 0
	global_load_lds_dwordx4 v[56:57], off
	ds_read_b128 v[56:59], v193 offset:0x2000
	s_waitcnt lgkmcnt(6)
	s_setprio 1
	v_mfma_f32_16x16x32_bf16 v[60:63], v[24:27], v[0:3], 0
	v_mfma_f32_16x16x32_bf16 v[64:67], v[24:27], v[4:7], 0
	v_mfma_f32_16x16x32_bf16 v[68:71], v[24:27], v[8:11], 0
	v_mfma_f32_16x16x32_bf16 v[24:27], v[24:27], v[12:15], 0
	s_setprio 0
	v_mov_b32_e32 v72, v180
	v_mov_b32_e32 v73, v172
	v_lshl_add_u64 v[72:73], v[72:73], 1, s[24:25]
	v_readfirstlane_b32 s13, v200
	v_lshl_add_u64 v[72:73], v[72:73], 0, s[62:63]
	s_mov_b32 m0, s13
	s_nop 0
	global_load_lds_dwordx4 v[72:73], off
	ds_read_b128 v[72:75], v193 offset:0x2800
	s_waitcnt lgkmcnt(6)
	s_setprio 1
	v_mfma_f32_16x16x32_bf16 v[76:79], v[40:43], v[0:3], 0
	v_mfma_f32_16x16x32_bf16 v[146:149], v[40:43], v[4:7], 0
	v_mfma_f32_16x16x32_bf16 v[150:153], v[40:43], v[8:11], 0
	v_mfma_f32_16x16x32_bf16 v[40:43], v[40:43], v[12:15], 0
	s_setprio 0
	v_mov_b32_e32 v80, v191
	v_mov_b32_e32 v81, v172
	v_lshl_add_u64 v[80:81], v[80:81], 1, s[24:25]
	v_readfirstlane_b32 s13, v201
	v_lshl_add_u64 v[80:81], v[80:81], 0, s[62:63]
	s_mov_b32 m0, s13
	s_nop 0
	global_load_lds_dwordx4 v[80:81], off
	ds_read_b128 v[80:83], v193 offset:0x3000
	s_waitcnt lgkmcnt(2)
	s_setprio 1
	v_mfma_f32_16x16x32_bf16 v[154:157], v[56:59], v[0:3], 0
	v_mfma_f32_16x16x32_bf16 v[158:161], v[56:59], v[4:7], 0
	v_mfma_f32_16x16x32_bf16 v[162:165], v[56:59], v[8:11], 0
	v_mfma_f32_16x16x32_bf16 v[166:169], v[56:59], v[12:15], 0
	s_setprio 0
	v_mov_b32_e32 v56, v176
	v_mov_b32_e32 v57, v172
	v_lshl_add_u64 v[56:57], v[56:57], 1, s[22:23]
	v_readfirstlane_b32 s13, v205
	v_lshl_add_u64 v[56:57], v[56:57], 0, s[62:63]
	s_mov_b32 m0, s13
	s_nop 0
	global_load_lds_dwordx4 v[56:57], off
	ds_read_b128 v[56:59], v193 offset:0x3800
	s_waitcnt lgkmcnt(2)
	s_setprio 1
	v_mfma_f32_16x16x32_bf16 v[206:209], v[72:75], v[0:3], 0
	v_mfma_f32_16x16x32_bf16 v[210:213], v[72:75], v[4:7], 0
	v_mfma_f32_16x16x32_bf16 v[214:217], v[72:75], v[8:11], 0
	v_mfma_f32_16x16x32_bf16 v[218:221], v[72:75], v[12:15], 0
	s_setprio 0
	v_mov_b32_e32 v72, v178
	v_mov_b32_e32 v73, v172
	v_lshl_add_u64 v[72:73], v[72:73], 1, s[22:23]
	v_readfirstlane_b32 s13, v202
	v_lshl_add_u64 v[72:73], v[72:73], 0, s[62:63]
	s_mov_b32 m0, s13
	s_nop 0
	global_load_lds_dwordx4 v[72:73], off
	ds_read_b128 v[72:75], v193 offset:0x400
	s_waitcnt lgkmcnt(2)
	s_setprio 1
	v_mfma_f32_16x16x32_bf16 v[222:225], v[80:83], v[0:3], 0
	v_mfma_f32_16x16x32_bf16 v[226:229], v[80:83], v[4:7], 0
	v_mfma_f32_16x16x32_bf16 v[230:233], v[80:83], v[8:11], 0
	v_mfma_f32_16x16x32_bf16 v[234:237], v[80:83], v[12:15], 0
	s_setprio 0
	v_mov_b32_e32 v80, v180
	v_mov_b32_e32 v81, v172
	v_lshl_add_u64 v[80:81], v[80:81], 1, s[22:23]
	v_readfirstlane_b32 s13, v203
	v_lshl_add_u64 v[80:81], v[80:81], 0, s[62:63]
	s_mov_b32 m0, s13
	s_nop 0
	global_load_lds_dwordx4 v[80:81], off
	ds_read_b128 v[80:83], v193 offset:0xc00
	s_waitcnt lgkmcnt(2)
; __device__ __forceinline__ float rsq_(float x) { return __builtin_amdgcn_rsqf(x); }
; #define WAIT_V(n) asm volatile("s_waitcnt vmcnt(%0)" ::"n"(n) : "memory")
; #define DSR(dst, addr, OFF) asm volatile("ds_read_b128 %0, %1 offset:%2" : "=&v"(dst) : "v"(addr), "i"(OFF) : "memory")
; template <int EPI>
; __device__ __forceinline__ void gemm_phase(const Params& p, const u16* __restrict__ A, const u16* __restrict__ Bt, int K, int nN,
;                            u16* __restrict__ Cout, int ldc) {
;     ...
;     for (int t = 0; t < nt; ++t) {
;       const int cur = t & 1, nb = cur ^ 1;
;       const bool last = (t + 1 == nt);
;       const bool dostage = !last || has_next;
;       const u16* pa = last ? Abn : Ab + (t + 1) * BK;
;       const u16* pb = last ? Bbn : Bb + (t + 1) * BK;
;       bf16x8 Ar[3], Bq[2][4];
;       const unsigned la_u = lds0 + (unsigned)(cur * STAGE_B + aoff), lb_u = lds0 + (unsigned)(cur * STAGE_B + boff);
;     ...
;       DSR(Bq[0][0], lb_u, 0); DSR(Bq[0][1], lb_u, 2048); DSR(Bq[0][2], lb_u, 4096); DSR(Bq[0][3], lb_u, 6144);
;       DSR(Ar[0], la_u, 0); DSR(Ar[1], la_u, 2048);
;     ...
;       GSTEP(0, 2); GSTEP(1, 6); GSTEP(2, 6); GSTEP(3, 6); GSTEP(4, 2); GSTEP(5, 2); GSTEP(6, 2); GSTEP(7, 2);
;       GSTEP(8, 2); GSTEP(9, 2); GSTEP(10, 2); GSTEP(11, 2); GSTEP(12, 2); GSTEP(13, 2); GSTEP(14, 1); GSTEP(15, 0);
;       WAIT_V(0);
;       if (EPI != EPI_SS && t == 0 && tid < 256) rsl[tid] = rsq_(ssv * (1.f / DM) + EPS);
;       __syncthreads();
	s_setprio 1
	v_mfma_f32_16x16x32_bf16 v[0:3], v[56:59], v[0:3], 0
	v_mfma_f32_16x16x32_bf16 v[4:7], v[56:59], v[4:7], 0
	v_mfma_f32_16x16x32_bf16 v[238:241], v[56:59], v[8:11], 0
	v_mfma_f32_16x16x32_bf16 v[242:245], v[56:59], v[12:15], 0
	s_setprio 0
	v_mov_b32_e32 v8, v191
	v_mov_b32_e32 v9, v172
	v_lshl_add_u64 v[8:9], v[8:9], 1, s[22:23]
	v_readfirstlane_b32 s13, v204
	v_lshl_add_u64 v[8:9], v[8:9], 0, s[62:63]
	s_mov_b32 m0, s13
	s_nop 0
	global_load_lds_dwordx4 v[8:9], off
	ds_read_b128 v[8:11], v193 offset:0x1400
	s_waitcnt lgkmcnt(2)
	s_setprio 1
	v_mfma_f32_16x16x32_bf16 v[124:127], v[72:75], v[130:133], v[28:31]
	v_mfma_f32_16x16x32_bf16 v[120:123], v[72:75], v[134:137], v[32:35]
	v_mfma_f32_16x16x32_bf16 v[116:119], v[72:75], v[138:141], v[36:39]
	v_mfma_f32_16x16x32_bf16 v[112:115], v[72:75], v[142:145], v[16:19]
	s_setprio 0
	ds_read_b128 v[12:15], v193 offset:0x1c00
	s_waitcnt lgkmcnt(2)
	s_setprio 1
	v_mfma_f32_16x16x32_bf16 v[108:111], v[80:83], v[130:133], v[44:47]
	v_mfma_f32_16x16x32_bf16 v[104:107], v[80:83], v[134:137], v[48:51]
	v_mfma_f32_16x16x32_bf16 v[100:103], v[80:83], v[138:141], v[52:55]
	v_mfma_f32_16x16x32_bf16 v[96:99], v[80:83], v[142:145], v[20:23]
	s_setprio 0
	ds_read_b128 v[16:19], v193 offset:0x2400
	s_waitcnt lgkmcnt(2)
	s_setprio 1
	v_mfma_f32_16x16x32_bf16 v[92:95], v[8:11], v[130:133], v[60:63]
	v_mfma_f32_16x16x32_bf16 v[88:91], v[8:11], v[134:137], v[64:67]
	v_mfma_f32_16x16x32_bf16 v[84:87], v[8:11], v[138:141], v[68:71]
	v_mfma_f32_16x16x32_bf16 v[80:83], v[8:11], v[142:145], v[24:27]
	s_setprio 0
	ds_read_b128 v[8:11], v193 offset:0x2c00
	s_waitcnt lgkmcnt(2)
	s_setprio 1
	v_mfma_f32_16x16x32_bf16 v[76:79], v[12:15], v[130:133], v[76:79]
	v_mfma_f32_16x16x32_bf16 v[72:75], v[12:15], v[134:137], v[146:149]
	v_mfma_f32_16x16x32_bf16 v[68:71], v[12:15], v[138:141], v[150:153]
	v_mfma_f32_16x16x32_bf16 v[64:67], v[12:15], v[142:145], v[40:43]
	s_setprio 0
	ds_read_b128 v[12:15], v193 offset:0x3400
	s_waitcnt lgkmcnt(2)
	s_setprio 1
	v_mfma_f32_16x16x32_bf16 v[60:63], v[16:19], v[130:133], v[154:157]
	v_mfma_f32_16x16x32_bf16 v[56:59], v[16:19], v[134:137], v[158:161]
	v_mfma_f32_16x16x32_bf16 v[52:55], v[16:19], v[138:141], v[162:165]
	v_mfma_f32_16x16x32_bf16 v[48:51], v[16:19], v[142:145], v[166:169]
	s_setprio 0
	ds_read_b128 v[146:149], v193 offset:0x3c00
	s_waitcnt lgkmcnt(2)
	s_setprio 1
	v_mfma_f32_16x16x32_bf16 v[44:47], v[8:11], v[130:133], v[206:209]
	v_mfma_f32_16x16x32_bf16 v[40:43], v[8:11], v[134:137], v[210:213]
	v_mfma_f32_16x16x32_bf16 v[36:39], v[8:11], v[138:141], v[214:217]
	v_mfma_f32_16x16x32_bf16 v[32:35], v[8:11], v[142:145], v[218:221]
	s_setprio 0
	s_waitcnt lgkmcnt(1)
	s_setprio 1
	v_mfma_f32_16x16x32_bf16 v[28:31], v[12:15], v[130:133], v[222:225]
	v_mfma_f32_16x16x32_bf16 v[24:27], v[12:15], v[134:137], v[226:229]
	v_mfma_f32_16x16x32_bf16 v[20:23], v[12:15], v[138:141], v[230:233]
	v_mfma_f32_16x16x32_bf16 v[16:19], v[12:15], v[142:145], v[234:237]
	s_setprio 0
	s_waitcnt lgkmcnt(0)
	s_setprio 1
	v_mfma_f32_16x16x32_bf16 v[12:15], v[146:149], v[130:133], v[0:3]
	v_mfma_f32_16x16x32_bf16 v[8:11], v[146:149], v[134:137], v[4:7]
	v_mfma_f32_16x16x32_bf16 v[4:7], v[146:149], v[138:141], v[238:241]
	v_mfma_f32_16x16x32_bf16 v[0:3], v[146:149], v[142:145], v[242:245]
	s_setprio 0
	s_waitcnt vmcnt(0)
	s_and_saveexec_b64 s[22:23], s[0:1]
	v_fmamk_f32 v128, v128, 0x3a800000, v183
	s_nop 0
	v_rsq_f32_e32 v128, v128
	s_nop 0
	ds_write_b32 v195, v128
	s_or_b64 exec, exec, s[22:23]
	s_add_u32 s13, s35, s20
	s_addc_u32 s24, s36, s21
	s_add_u32 s25, s37, s2
	s_addc_u32 s26, s38, s3
	s_mov_b32 s27, -15
	s_waitcnt vmcnt(0) lgkmcnt(0)
	s_barrier
	v_or_b32_e32 v208, 0x10000, v194
	v_add_u32_e32 v206, 0x10000, v193
	ds_read_b128 v[212:215], v208 offset:0
	ds_read_b128 v[216:219], v208 offset:2048
	ds_read_b128 v[220:223], v208 offset:4096
	ds_read_b128 v[224:227], v208 offset:6144
	ds_read_b128 v[228:231], v206 offset:0
	ds_read_b128 v[168:171], v206 offset:2048
	ds_read_b128 v[160:163], v206 offset:4096
	v_readfirstlane_b32 s40, v175
	v_lshlrev_b32_e32 v232, 1, v176
	v_lshlrev_b32_e32 v233, 1, v178
	v_lshlrev_b32_e32 v234, 1, v180
	v_lshlrev_b32_e32 v235, 1, v191
	s_cmp_lg_u32 s27, -1
	s_cselect_b32 s22, s25, s16
	s_cselect_b32 s23, s26, s17
	s_cselect_b32 s20, s13, s18
	s_cselect_b32 s21, s24, s19
	s_cselect_b64 vcc, -1, s[10:11]
	v_readfirstlane_b32 s28, v175
	s_nop 3
	s_lshr_b32 s28, s28, 12
	s_cmp_eq_u32 s28, 1
	s_cbranch_scc1 .Lgub_head

; template <int EPI>
; __device__ __forceinline__ void gemm_phase(const Params& p, const u16* __restrict__ A, const u16* __restrict__ Bt, int K, int nN,
;                            u16* __restrict__ Cout, int ldc) {
;     ...
;       GSTEP(0, 2); GSTEP(1, 6); GSTEP(2, 6); GSTEP(3, 6); GSTEP(4, 2); GSTEP(5, 2); GSTEP(6, 2); GSTEP(7, 2);
;       GSTEP(8, 2); GSTEP(9, 2); GSTEP(10, 2); GSTEP(11, 2); GSTEP(12, 2); GSTEP(13, 2); GSTEP(14, 1); GSTEP(15, 0);
.Lgub_head:
	s_waitcnt lgkmcnt(2)
	s_setprio 2
	v_mfma_f32_16x16x32_bf16 v[124:127], v[228:231], v[212:215], v[124:127]
	v_mfma_f32_16x16x32_bf16 v[120:123], v[228:231], v[216:219], v[120:123]
	v_mfma_f32_16x16x32_bf16 v[116:119], v[228:231], v[220:223], v[116:119]
	v_mfma_f32_16x16x32_bf16 v[112:115], v[228:231], v[224:227], v[112:115]
	s_setprio 1
	s_cbranch_vccz .Lgub_sk13
	s_mov_b32 m0, s40
	s_nop 0
	global_load_lds_dwordx4 v232, s[22:23]
	s_add_u32 m0, s40, 0x2000
	s_nop 0
	global_load_lds_dwordx4 v233, s[22:23]
.Lgub_sk13:
	ds_read_b128 v[164:167], v206 offset:6144
	ds_read_b128 v[128:131], v208 offset:1024
	ds_read_b128 v[132:135], v208 offset:3072
	ds_read_b128 v[136:139], v208 offset:5120
	ds_read_b128 v[140:143], v208 offset:7168
	s_waitcnt lgkmcnt(6)
	s_setprio 2
	v_mfma_f32_16x16x32_bf16 v[108:111], v[168:171], v[212:215], v[108:111]
	v_mfma_f32_16x16x32_bf16 v[104:107], v[168:171], v[216:219], v[104:107]
	v_mfma_f32_16x16x32_bf16 v[100:103], v[168:171], v[220:223], v[100:103]
	v_mfma_f32_16x16x32_bf16 v[96:99], v[168:171], v[224:227], v[96:99]
	s_setprio 1
	s_cbranch_vccz .Lgub_sk14
	s_add_u32 m0, s40, 0x4000
	s_nop 0
	global_load_lds_dwordx4 v234, s[22:23]
	s_add_u32 m0, s40, 0x6000
	s_nop 0
	global_load_lds_dwordx4 v235, s[22:23]
.Lgub_sk14:
	ds_read_b128 v[168:171], v206 offset:8192
	s_waitcnt lgkmcnt(6)
	s_setprio 2
	v_mfma_f32_16x16x32_bf16 v[92:95], v[160:163], v[212:215], v[92:95]
	v_mfma_f32_16x16x32_bf16 v[88:91], v[160:163], v[216:219], v[88:91]
	v_mfma_f32_16x16x32_bf16 v[84:87], v[160:163], v[220:223], v[84:87]
	v_mfma_f32_16x16x32_bf16 v[80:83], v[160:163], v[224:227], v[80:83]
	s_setprio 1
	s_cbranch_vccz .Lgub_sk15
	s_add_u32 m0, s40, 0x8000
	s_nop 0
	global_load_lds_dwordx4 v232, s[20:21]
	s_add_u32 m0, s40, 0xa000
	s_nop 0
	global_load_lds_dwordx4 v233, s[20:21]
.Lgub_sk15:
	ds_read_b128 v[160:163], v206 offset:10240
	s_waitcnt lgkmcnt(6)
	s_setprio 2
	v_mfma_f32_16x16x32_bf16 v[76:79], v[164:167], v[212:215], v[76:79]
	v_mfma_f32_16x16x32_bf16 v[72:75], v[164:167], v[216:219], v[72:75]
	v_mfma_f32_16x16x32_bf16 v[68:71], v[164:167], v[220:223], v[68:71]
	v_mfma_f32_16x16x32_bf16 v[64:67], v[164:167], v[224:227], v[64:67]
	s_setprio 1
	s_cbranch_vccz .Lgub_sk16
	s_add_u32 m0, s40, 0xc000
	s_nop 0
	global_load_lds_dwordx4 v234, s[20:21]
	s_add_u32 m0, s40, 0xe000
	s_nop 0
	global_load_lds_dwordx4 v235, s[20:21]
; __device__ __forceinline__ float rsq_(float x) { return __builtin_amdgcn_rsqf(x); }
; #define WAIT_V(n) asm volatile("s_waitcnt vmcnt(%0)" ::"n"(n) : "memory")
; template <int EPI>
; __device__ __forceinline__ void gemm_phase(const Params& p, const u16* __restrict__ A, const u16* __restrict__ Bt, int K, int nN,
;                            u16* __restrict__ Cout, int ldc) {
;     ...
;       GSTEP(0, 2); GSTEP(1, 6); GSTEP(2, 6); GSTEP(3, 6); GSTEP(4, 2); GSTEP(5, 2); GSTEP(6, 2); GSTEP(7, 2);
;       GSTEP(8, 2); GSTEP(9, 2); GSTEP(10, 2); GSTEP(11, 2); GSTEP(12, 2); GSTEP(13, 2); GSTEP(14, 1); GSTEP(15, 0);
;       WAIT_V(0);
;       if (EPI != EPI_SS && t == 0 && tid < 256) rsl[tid] = rsq_(ssv * (1.f / DM) + EPS);
;       __syncthreads();
;     }
.Lgub_sk16:
	ds_read_b128 v[164:167], v206 offset:12288
	s_waitcnt lgkmcnt(2)
	s_setprio 2
	v_mfma_f32_16x16x32_bf16 v[60:63], v[168:171], v[212:215], v[60:63]
	v_mfma_f32_16x16x32_bf16 v[56:59], v[168:171], v[216:219], v[56:59]
	v_mfma_f32_16x16x32_bf16 v[52:55], v[168:171], v[220:223], v[52:55]
	v_mfma_f32_16x16x32_bf16 v[48:51], v[168:171], v[224:227], v[48:51]
	s_setprio 1
	ds_read_b128 v[168:171], v206 offset:14336
	s_waitcnt lgkmcnt(2)
	s_setprio 2
	v_mfma_f32_16x16x32_bf16 v[44:47], v[160:163], v[212:215], v[44:47]
	v_mfma_f32_16x16x32_bf16 v[40:43], v[160:163], v[216:219], v[40:43]
	v_mfma_f32_16x16x32_bf16 v[36:39], v[160:163], v[220:223], v[36:39]
	v_mfma_f32_16x16x32_bf16 v[32:35], v[160:163], v[224:227], v[32:35]
	s_setprio 1
	ds_read_b128 v[160:163], v206 offset:1024
	s_waitcnt lgkmcnt(2)
	s_setprio 2
	v_mfma_f32_16x16x32_bf16 v[28:31], v[164:167], v[212:215], v[28:31]
	v_mfma_f32_16x16x32_bf16 v[24:27], v[164:167], v[216:219], v[24:27]
	v_mfma_f32_16x16x32_bf16 v[20:23], v[164:167], v[220:223], v[20:23]
	v_mfma_f32_16x16x32_bf16 v[16:19], v[164:167], v[224:227], v[16:19]
	s_setprio 1
	ds_read_b128 v[164:167], v206 offset:3072
	s_waitcnt lgkmcnt(2)
	s_setprio 2
	v_mfma_f32_16x16x32_bf16 v[12:15], v[168:171], v[212:215], v[12:15]
	v_mfma_f32_16x16x32_bf16 v[8:11], v[168:171], v[216:219], v[8:11]
	v_mfma_f32_16x16x32_bf16 v[4:7], v[168:171], v[220:223], v[4:7]
	v_mfma_f32_16x16x32_bf16 v[0:3], v[168:171], v[224:227], v[0:3]
	s_setprio 1
	ds_read_b128 v[144:147], v206 offset:5120
	s_waitcnt lgkmcnt(2)
	s_setprio 2
	v_mfma_f32_16x16x32_bf16 v[124:127], v[160:163], v[128:131], v[124:127]
	v_mfma_f32_16x16x32_bf16 v[120:123], v[160:163], v[132:135], v[120:123]
	v_mfma_f32_16x16x32_bf16 v[116:119], v[160:163], v[136:139], v[116:119]
	v_mfma_f32_16x16x32_bf16 v[112:115], v[160:163], v[140:143], v[112:115]
	s_setprio 1
	ds_read_b128 v[148:151], v206 offset:7168
	s_waitcnt lgkmcnt(2)
	s_setprio 2
	v_mfma_f32_16x16x32_bf16 v[108:111], v[164:167], v[128:131], v[108:111]
	v_mfma_f32_16x16x32_bf16 v[104:107], v[164:167], v[132:135], v[104:107]
	v_mfma_f32_16x16x32_bf16 v[100:103], v[164:167], v[136:139], v[100:103]
	v_mfma_f32_16x16x32_bf16 v[96:99], v[164:167], v[140:143], v[96:99]
	s_setprio 1
	ds_read_b128 v[152:155], v206 offset:9216
	s_waitcnt lgkmcnt(2)
	s_setprio 2
	v_mfma_f32_16x16x32_bf16 v[92:95], v[144:147], v[128:131], v[92:95]
	v_mfma_f32_16x16x32_bf16 v[88:91], v[144:147], v[132:135], v[88:91]
	v_mfma_f32_16x16x32_bf16 v[84:87], v[144:147], v[136:139], v[84:87]
	v_mfma_f32_16x16x32_bf16 v[80:83], v[144:147], v[140:143], v[80:83]
	s_setprio 1
	ds_read_b128 v[144:147], v206 offset:11264
	s_waitcnt lgkmcnt(2)
	s_setprio 2
	v_mfma_f32_16x16x32_bf16 v[76:79], v[148:151], v[128:131], v[76:79]
	v_mfma_f32_16x16x32_bf16 v[72:75], v[148:151], v[132:135], v[72:75]
	v_mfma_f32_16x16x32_bf16 v[68:71], v[148:151], v[136:139], v[68:71]
	v_mfma_f32_16x16x32_bf16 v[64:67], v[148:151], v[140:143], v[64:67]
	s_setprio 1
	ds_read_b128 v[148:151], v206 offset:13312
	s_waitcnt lgkmcnt(2)
	s_setprio 2
	v_mfma_f32_16x16x32_bf16 v[60:63], v[152:155], v[128:131], v[60:63]
	v_mfma_f32_16x16x32_bf16 v[56:59], v[152:155], v[132:135], v[56:59]
	v_mfma_f32_16x16x32_bf16 v[52:55], v[152:155], v[136:139], v[52:55]
	v_mfma_f32_16x16x32_bf16 v[48:51], v[152:155], v[140:143], v[48:51]
	s_setprio 1
	ds_read_b128 v[152:155], v206 offset:15360
	s_waitcnt lgkmcnt(2)
	s_setprio 2
	v_mfma_f32_16x16x32_bf16 v[44:47], v[144:147], v[128:131], v[44:47]
	v_mfma_f32_16x16x32_bf16 v[40:43], v[144:147], v[132:135], v[40:43]
	v_mfma_f32_16x16x32_bf16 v[36:39], v[144:147], v[136:139], v[36:39]
	v_mfma_f32_16x16x32_bf16 v[32:35], v[144:147], v[140:143], v[32:35]
	s_setprio 1
	s_waitcnt vmcnt(0) lgkmcnt(0)
	s_barrier
	v_xor_b32_e32 v208, 0x10000, v208
	v_xor_b32_e32 v206, 0x10000, v206
	ds_read_b128 v[212:215], v208 offset:0
	ds_read_b128 v[216:219], v208 offset:2048
	ds_read_b128 v[220:223], v208 offset:4096
	ds_read_b128 v[224:227], v208 offset:6144
	ds_read_b128 v[228:231], v206 offset:0
	ds_read_b128 v[168:171], v206 offset:2048
	ds_read_b128 v[160:163], v206 offset:4096
	s_add_u32 s25, s25, 0x80
	s_addc_u32 s26, s26, 0
	s_add_u32 s13, s13, 0x80
	s_addc_u32 s24, s24, 0
	s_xor_b32 s40, s40, 0x10000
	s_add_i32 s27, s27, 1
	s_cmp_lg_u32 s27, -1
	s_cselect_b32 s22, s25, s16
	s_cselect_b32 s23, s26, s17
	s_cselect_b32 s20, s13, s18
	s_cselect_b32 s21, s24, s19
	s_cselect_b64 vcc, -1, s[10:11]
	s_cmp_eq_u32 s27, 0
	s_cselect_b64 vcc, 0, vcc
	s_setprio 2
	v_mfma_f32_16x16x32_bf16 v[28:31], v[148:151], v[128:131], v[28:31]
	v_mfma_f32_16x16x32_bf16 v[24:27], v[148:151], v[132:135], v[24:27]
	v_mfma_f32_16x16x32_bf16 v[20:23], v[148:151], v[136:139], v[20:23]
	v_mfma_f32_16x16x32_bf16 v[16:19], v[148:151], v[140:143], v[16:19]
	s_setprio 1
	s_setprio 2
	v_mfma_f32_16x16x32_bf16 v[12:15], v[152:155], v[128:131], v[12:15]
	v_mfma_f32_16x16x32_bf16 v[8:11], v[152:155], v[132:135], v[8:11]
	v_mfma_f32_16x16x32_bf16 v[4:7], v[152:155], v[136:139], v[4:7]
	v_mfma_f32_16x16x32_bf16 v[0:3], v[152:155], v[140:143], v[0:3]
	s_setprio 1
	s_cmp_lg_u32 s27, 0
	s_cbranch_scc1 .Lgub_head
	s_waitcnt lgkmcnt(0)
	s_setprio 0
	s_branch .LBB0_1126
